# dilated attention mask: per-lane phase test hoisted and per-element range test reduced to (q-off)<=128 (identical predicate, 6->3 VALU per element); bit-identical outputs
# baseline (speedup 1.0000x reference)
; template <int MODE>
; __device__ __forceinline__ void att_smpv(f32x16 (&s)[2], f32x16 (&o)[4], float& mrun, float& lrun, float& Rrun, int tq, int tqmin, int tok0, int st, int dil, int h, int lane, const LAS unsigned char* vb) {
;     ...
;         const bool need_mask = (MODE == 0) || (tok0 + 63 > tqmin);
;         if (need_mask) {
; #pragma unroll
;             for (int kk = 0; kk < 2; ++kk)
; #pragma unroll
;                 for (int e = 0; e < 16; ++e) { const int d = d0 - st * (32 * kk + 8 * (e >> 2) + (e & 3));
;                     const bool ok = (MODE == 0) ? ((unsigned)d <= 128u * (unsigned)dil && (d & (dil - 1)) == 0) : (d >= 0);
;                     s[kk][e] = ok ? s[kk][e] : -INFINITY; }
;         }
;         float mx = fmaxf(fmaxf(s[0][0], s[1][0]), fmaxf(s[0][1], s[1][1]));
; #pragma unroll
;         for (int e = 2; e < 16; e += 2) { mx = fmaxf(fmaxf(mx, s[0][e]), s[1][e]); mx = fmaxf(fmaxf(mx, s[0][e + 1]), s[1][e + 1]); }
;         mx = fmaxf(mx, xhalf(mx, h));
;         if (__any(mx > mrun)) {
.LBB0_293:
	s_mul_i32 s8, s51, 63
	s_lshl_b32 s52, s51, 7
	s_add_i32 s8, s53, s8
	s_sub_i32 s9, s13, s52
	s_cmp_lt_i32 s8, s9
	s_cselect_b64 s[8:9], -1, 0
	s_cmp_gt_i32 s53, s20
	s_cselect_b64 s[54:55], -1, 0
	s_or_b64 s[8:9], s[8:9], s[54:55]
	s_and_b64 vcc, exec, s[8:9]
	s_cbranch_vccnz .LBB0_297
	v_add_u32_e32 v0, s48, v136
	v_add_u32_e32 v70, v0, v137
	v_add_u32_e32 v74, v0, v138
	ds_read_b128 v[66:69], v70
	ds_read_b128 v[70:73], v70 offset:8192
	ds_read_b128 v[178:181], v74
	ds_read_b128 v[182:185], v74 offset:8192
	s_waitcnt lgkmcnt(0)
	v_mfma_f32_32x32x16_bf16 v[82:97], v[66:69], v[98:101], 0
	v_mfma_f32_32x32x16_bf16 v[66:81], v[70:73], v[98:101], 0
	v_add_u32_e32 v190, v0, v170
	ds_read_b128 v[186:189], v190
	ds_read_b128 v[190:193], v190 offset:8192
	v_mfma_f32_32x32x16_bf16 v[82:97], v[178:181], v[102:105], v[82:97]
	v_mfma_f32_32x32x16_bf16 v[66:81], v[182:185], v[102:105], v[66:81]
	v_add_u32_e32 v182, v0, v171
	ds_read_b128 v[178:181], v182
	ds_read_b128 v[182:185], v182 offset:8192
	s_waitcnt lgkmcnt(0)
	v_mfma_f32_32x32x16_bf16 v[82:97], v[186:189], v[106:109], v[82:97]
	v_mfma_f32_32x32x16_bf16 v[66:81], v[190:193], v[106:109], v[66:81]
	v_add_u32_e32 v190, v0, v172
	ds_read_b128 v[186:189], v190
	ds_read_b128 v[190:193], v190 offset:8192
	v_mfma_f32_32x32x16_bf16 v[82:97], v[178:181], v[110:113], v[82:97]
	v_mfma_f32_32x32x16_bf16 v[66:81], v[182:185], v[110:113], v[66:81]
	v_add_u32_e32 v182, v0, v173
	ds_read_b128 v[178:181], v182
	ds_read_b128 v[182:185], v182 offset:8192
	s_waitcnt lgkmcnt(0)
	v_mfma_f32_32x32x16_bf16 v[82:97], v[186:189], v[114:117], v[82:97]
	v_mfma_f32_32x32x16_bf16 v[66:81], v[190:193], v[114:117], v[66:81]
	v_add_u32_e32 v190, v0, v174
	ds_read_b128 v[186:189], v190
	ds_read_b128 v[190:193], v190 offset:8192
	v_mfma_f32_32x32x16_bf16 v[82:97], v[178:181], v[118:121], v[82:97]
	v_mfma_f32_32x32x16_bf16 v[66:81], v[182:185], v[118:121], v[66:81]
	v_add_u32_e32 v0, v0, v175
	ds_read_b128 v[178:181], v0
	ds_read_b128 v[182:185], v0 offset:8192
	s_waitcnt lgkmcnt(0)
	v_mfma_f32_32x32x16_bf16 v[82:97], v[186:189], v[122:125], v[82:97]
	v_mfma_f32_32x32x16_bf16 v[66:81], v[190:193], v[122:125], v[66:81]
	v_mfma_f32_32x32x16_bf16 v[82:97], v[178:181], v[126:129], v[82:97]
	v_mfma_f32_32x32x16_bf16 v[66:81], v[182:185], v[126:129], v[66:81]
	v_subrev_u32_e32 v180, s53, v130
	v_mul_u32_u24_e32 v0, s51, v135
	s_add_i32 s53, s51, -1
	v_sub_u32_e32 v244, v180, v0
	s_ff1_i32_b32 s54, s51
	v_and_b32_e32 v245, s53, v244
	v_lshrrev_b32_e32 v244, s54, v244
	v_cmp_eq_u32_e32 vcc, 0, v245
	s_movk_i32 s54, 0x80
	v_mov_b32_e32 v245, 0x7fffffff
	s_nop 0
	v_cndmask_b32_e32 v244, v245, v244, vcc
	v_subrev_u32_e32 v245, 0, v244
	v_cmp_ge_u32_e32 vcc, s54, v245
	v_subrev_u32_e32 v246, 1, v244
	v_cmp_ge_u32_e64 s[8:9], s54, v246
	v_cndmask_b32_e32 v0, v214, v82, vcc
	v_subrev_u32_e32 v245, 2, v244
	v_cmp_ge_u32_e32 vcc, s54, v245
	v_cndmask_b32_e64 v83, v214, v83, s[8:9]
	v_subrev_u32_e32 v246, 3, v244
	v_cmp_ge_u32_e64 s[8:9], s54, v246
	v_cndmask_b32_e32 v82, v214, v84, vcc
	v_subrev_u32_e32 v245, 8, v244
	v_cmp_ge_u32_e32 vcc, s54, v245
	v_cndmask_b32_e64 v85, v214, v85, s[8:9]
	v_subrev_u32_e32 v246, 9, v244
	v_cmp_ge_u32_e64 s[8:9], s54, v246
	v_cndmask_b32_e32 v84, v214, v86, vcc
	v_subrev_u32_e32 v245, 10, v244
	v_cmp_ge_u32_e32 vcc, s54, v245
	v_cndmask_b32_e64 v87, v214, v87, s[8:9]
	v_subrev_u32_e32 v246, 11, v244
	v_cmp_ge_u32_e64 s[8:9], s54, v246
	v_cndmask_b32_e32 v86, v214, v88, vcc
	v_subrev_u32_e32 v245, 16, v244
	v_cmp_ge_u32_e32 vcc, s54, v245
	v_cndmask_b32_e64 v89, v214, v89, s[8:9]
	v_subrev_u32_e32 v246, 17, v244
	v_cmp_ge_u32_e64 s[8:9], s54, v246
	v_cndmask_b32_e32 v88, v214, v90, vcc
	v_subrev_u32_e32 v245, 18, v244
	v_cmp_ge_u32_e32 vcc, s54, v245
	v_cndmask_b32_e64 v91, v214, v91, s[8:9]
	v_subrev_u32_e32 v246, 19, v244
	v_cmp_ge_u32_e64 s[8:9], s54, v246
	v_cndmask_b32_e32 v90, v214, v92, vcc
	v_subrev_u32_e32 v245, 24, v244
	v_cmp_ge_u32_e32 vcc, s54, v245
	v_cndmask_b32_e64 v93, v214, v93, s[8:9]
	v_subrev_u32_e32 v246, 25, v244
	v_cmp_ge_u32_e64 s[8:9], s54, v246
	v_cndmask_b32_e32 v92, v214, v94, vcc
	v_subrev_u32_e32 v245, 26, v244
	v_cmp_ge_u32_e32 vcc, s54, v245
	v_cndmask_b32_e64 v95, v214, v95, s[8:9]
	v_subrev_u32_e32 v246, 27, v244
	v_cmp_ge_u32_e64 s[8:9], s54, v246
	v_cndmask_b32_e32 v94, v214, v96, vcc
	v_subrev_u32_e32 v245, 32, v244
	v_cmp_ge_u32_e32 vcc, s54, v245
	v_cndmask_b32_e64 v96, v214, v97, s[8:9]
	v_subrev_u32_e32 v246, 33, v244
	v_cmp_ge_u32_e64 s[8:9], s54, v246
	v_cndmask_b32_e32 v66, v214, v66, vcc
	v_subrev_u32_e32 v245, 34, v244
	v_cmp_ge_u32_e32 vcc, s54, v245
	v_cndmask_b32_e64 v97, v214, v67, s[8:9]
	v_subrev_u32_e32 v246, 35, v244
	v_cmp_ge_u32_e64 s[8:9], s54, v246
	v_cndmask_b32_e32 v67, v214, v68, vcc
	v_subrev_u32_e32 v245, 40, v244
	v_cmp_ge_u32_e32 vcc, s54, v245
	v_cndmask_b32_e64 v178, v214, v69, s[8:9]
	v_subrev_u32_e32 v246, 41, v244
	v_cmp_ge_u32_e64 s[8:9], s54, v246
	v_cndmask_b32_e32 v68, v214, v70, vcc
	v_subrev_u32_e32 v245, 42, v244
	v_cmp_ge_u32_e32 vcc, s54, v245
	v_cndmask_b32_e64 v179, v214, v71, s[8:9]
	v_subrev_u32_e32 v246, 43, v244
	v_cmp_ge_u32_e64 s[8:9], s54, v246
	v_cndmask_b32_e32 v69, v214, v72, vcc
	v_subrev_u32_e32 v245, 48, v244
	v_cmp_ge_u32_e32 vcc, s54, v245
	v_cndmask_b32_e64 v73, v214, v73, s[8:9]
	v_subrev_u32_e32 v246, 49, v244
	v_cmp_ge_u32_e64 s[8:9], s54, v246
	v_cndmask_b32_e32 v70, v214, v74, vcc
	v_subrev_u32_e32 v245, 50, v244
	v_cmp_ge_u32_e32 vcc, s54, v245
	v_cndmask_b32_e64 v75, v214, v75, s[8:9]
	v_subrev_u32_e32 v246, 51, v244
	v_cmp_ge_u32_e64 s[8:9], s54, v246
	v_cndmask_b32_e32 v71, v214, v76, vcc
	v_subrev_u32_e32 v245, 56, v244
	v_cmp_ge_u32_e32 vcc, s54, v245
	v_cndmask_b32_e64 v76, v214, v77, s[8:9]
	v_subrev_u32_e32 v246, 57, v244
	v_cmp_ge_u32_e64 s[8:9], s54, v246
	v_cndmask_b32_e32 v72, v214, v78, vcc
	v_subrev_u32_e32 v245, 58, v244
	v_cmp_ge_u32_e32 vcc, s54, v245
	v_cndmask_b32_e64 v77, v214, v79, s[8:9]
	v_subrev_u32_e32 v246, 59, v244
	v_cmp_ge_u32_e64 s[8:9], s54, v246
	v_cndmask_b32_e32 v74, v214, v80, vcc
	s_nop 1
	v_cndmask_b32_e64 v78, v214, v81, s[8:9]
	s_mul_i32 s54, s51, 5
	v_max_f32_e32 v79, v97, v97
	v_max_f32_e32 v80, v83, v83
	v_max_f32_e32 v79, v80, v79
	v_max3_f32 v79, v0, v66, v79
	v_max3_f32 v79, v79, v82, v67
	v_max3_f32 v79, v79, v85, v178
	v_max3_f32 v79, v79, v84, v68
	v_max3_f32 v79, v79, v87, v179
	v_max3_f32 v79, v79, v86, v69
	v_max3_f32 v79, v79, v89, v73
	v_max3_f32 v79, v79, v88, v70
	v_max3_f32 v79, v79, v91, v75
	v_max3_f32 v79, v79, v90, v71
	v_max3_f32 v79, v79, v93, v76
	v_max3_f32 v79, v79, v92, v72
	v_max3_f32 v79, v79, v95, v77
	v_max3_f32 v79, v79, v94, v74
	v_max3_f32 v79, v79, v96, v78
	v_mov_b32_e32 v80, v79
	v_mov_b32_e32 v81, v79
	s_nop 1
	v_permlane32_swap_b32_e32 v80, v81
	v_cndmask_b32_e64 v80, v80, v81, s[6:7]
	v_max_f32_e32 v80, v80, v80
	v_max_f32_e32 v79, v79, v80
	v_cmp_gt_f32_e32 vcc, v79, v177
	s_cbranch_vccz .LBB0_296
; template <int MODE>
; __device__ __forceinline__ void att_smpv(f32x16 (&s)[2], f32x16 (&o)[4], float& mrun, float& lrun, float& Rrun, int tq, int tqmin, int tok0, int st, int dil, int h, int lane, const LAS unsigned char* vb) {
;     ...
;         if (__any(mx > mrun)) {
;             const float mnew = fmaxf(mrun, mx), alpha = __builtin_amdgcn_exp2f(mrun - mnew); mrun = mnew; lrun *= alpha;
; #pragma unroll
;             for (int b = 0; b < 4; ++b)
; #pragma unroll
;                 for (int e = 0; e < 16; ++e) o[b][e] *= alpha;
;         }
	v_max_f32_e32 v79, v79, v79
	v_max_f32_e32 v80, v177, v177
	v_max_f32_e32 v79, v80, v79
	v_sub_f32_e32 v80, v177, v79
	v_exp_f32_e32 v80, v80
	v_mov_b32_e32 v177, v79
	v_mul_f32_e32 v176, v176, v80
	v_pk_mul_f32 v[64:65], v[64:65], v[80:81] op_sel_hi:[1,0]
	v_pk_mul_f32 v[62:63], v[62:63], v[80:81] op_sel_hi:[1,0]
	v_pk_mul_f32 v[60:61], v[60:61], v[80:81] op_sel_hi:[1,0]
	v_pk_mul_f32 v[58:59], v[58:59], v[80:81] op_sel_hi:[1,0]
	v_pk_mul_f32 v[56:57], v[56:57], v[80:81] op_sel_hi:[1,0]
	v_pk_mul_f32 v[54:55], v[54:55], v[80:81] op_sel_hi:[1,0]
	v_pk_mul_f32 v[52:53], v[52:53], v[80:81] op_sel_hi:[1,0]
	v_pk_mul_f32 v[50:51], v[50:51], v[80:81] op_sel_hi:[1,0]
	v_pk_mul_f32 v[48:49], v[48:49], v[80:81] op_sel_hi:[1,0]
	v_pk_mul_f32 v[46:47], v[46:47], v[80:81] op_sel_hi:[1,0]
	v_pk_mul_f32 v[44:45], v[44:45], v[80:81] op_sel_hi:[1,0]
	v_pk_mul_f32 v[42:43], v[42:43], v[80:81] op_sel_hi:[1,0]
	v_pk_mul_f32 v[40:41], v[40:41], v[80:81] op_sel_hi:[1,0]
	v_pk_mul_f32 v[38:39], v[38:39], v[80:81] op_sel_hi:[1,0]
	v_pk_mul_f32 v[36:37], v[36:37], v[80:81] op_sel_hi:[1,0]
	v_pk_mul_f32 v[34:35], v[34:35], v[80:81] op_sel_hi:[1,0]
	v_pk_mul_f32 v[32:33], v[32:33], v[80:81] op_sel_hi:[1,0]
	v_pk_mul_f32 v[30:31], v[30:31], v[80:81] op_sel_hi:[1,0]
	v_pk_mul_f32 v[28:29], v[28:29], v[80:81] op_sel_hi:[1,0]
	v_pk_mul_f32 v[26:27], v[26:27], v[80:81] op_sel_hi:[1,0]
	v_pk_mul_f32 v[24:25], v[24:25], v[80:81] op_sel_hi:[1,0]
	v_pk_mul_f32 v[22:23], v[22:23], v[80:81] op_sel_hi:[1,0]
	v_pk_mul_f32 v[20:21], v[20:21], v[80:81] op_sel_hi:[1,0]
	v_pk_mul_f32 v[18:19], v[18:19], v[80:81] op_sel_hi:[1,0]
	v_pk_mul_f32 v[16:17], v[16:17], v[80:81] op_sel_hi:[1,0]
	v_pk_mul_f32 v[14:15], v[14:15], v[80:81] op_sel_hi:[1,0]
	v_pk_mul_f32 v[12:13], v[12:13], v[80:81] op_sel_hi:[1,0]
	v_pk_mul_f32 v[10:11], v[10:11], v[80:81] op_sel_hi:[1,0]
	v_pk_mul_f32 v[8:9], v[8:9], v[80:81] op_sel_hi:[1,0]
	v_pk_mul_f32 v[6:7], v[6:7], v[80:81] op_sel_hi:[1,0]
	v_pk_mul_f32 v[4:5], v[4:5], v[80:81] op_sel_hi:[1,0]
	v_pk_mul_f32 v[2:3], v[2:3], v[80:81] op_sel_hi:[1,0]

; template <int DK, int MODE>
; __device__ __forceinline__ void attn_unit(LAS unsigned char* lds, const bf16_t* Q, int ldq, const bf16_t* Kp, int ldk, const bf16_t* Vp, int ldv, bf16_t* O, int ldo, int u0, int r4) {
;     ...
;             if (tok0 >= 0 && ATT_REL(tok0, st, dil)) { f32x16 s[2]; ATT_QK2(s[0], s[1], kb); att_smpv<MODE>(s, o, mrun, lrun, Rrun, tq, tqmin, tok0, st, dil, h, lane, kb + KBYTES); } }
.LBB0_306:
	s_mul_i32 s4, s28, 63
	s_add_i32 s5, s8, s4
	s_lshl_b32 s4, s28, 7
	s_sub_i32 s9, s13, s4
	s_cmp_lt_i32 s5, s9
	s_cselect_b64 s[50:51], -1, 0
	s_cmp_gt_i32 s8, s20
	s_cselect_b64 s[52:53], -1, 0
	s_or_b64 s[50:51], s[50:51], s[52:53]
	s_and_b64 vcc, exec, s[50:51]
	s_cbranch_vccnz .LBB0_310
	v_add_u32_e32 v0, s48, v136
	v_add_u32_e32 v70, v0, v137
	v_add_u32_e32 v74, v0, v138
	ds_read_b128 v[66:69], v70 offset:32768
	ds_read_b128 v[70:73], v70 offset:40960
	ds_read_b128 v[178:181], v74 offset:32768
	ds_read_b128 v[182:185], v74 offset:40960
	s_waitcnt lgkmcnt(0)
	v_mfma_f32_32x32x16_bf16 v[82:97], v[66:69], v[98:101], 0
	v_mfma_f32_32x32x16_bf16 v[66:81], v[70:73], v[98:101], 0
	v_add_u32_e32 v190, v0, v170
	ds_read_b128 v[186:189], v190 offset:32768
	ds_read_b128 v[190:193], v190 offset:40960
	v_mfma_f32_32x32x16_bf16 v[82:97], v[178:181], v[102:105], v[82:97]
	v_mfma_f32_32x32x16_bf16 v[66:81], v[182:185], v[102:105], v[66:81]
	v_add_u32_e32 v182, v0, v171
	ds_read_b128 v[178:181], v182 offset:32768
	ds_read_b128 v[182:185], v182 offset:40960
	s_waitcnt lgkmcnt(0)
	v_mfma_f32_32x32x16_bf16 v[82:97], v[186:189], v[106:109], v[82:97]
	v_mfma_f32_32x32x16_bf16 v[66:81], v[190:193], v[106:109], v[66:81]
	v_add_u32_e32 v190, v0, v172
	ds_read_b128 v[186:189], v190 offset:32768
	ds_read_b128 v[190:193], v190 offset:40960
	v_mfma_f32_32x32x16_bf16 v[82:97], v[178:181], v[110:113], v[82:97]
	v_mfma_f32_32x32x16_bf16 v[66:81], v[182:185], v[110:113], v[66:81]
	v_add_u32_e32 v182, v0, v173
	ds_read_b128 v[178:181], v182 offset:32768
	ds_read_b128 v[182:185], v182 offset:40960
	s_waitcnt lgkmcnt(0)
	v_mfma_f32_32x32x16_bf16 v[82:97], v[186:189], v[114:117], v[82:97]
	v_mfma_f32_32x32x16_bf16 v[66:81], v[190:193], v[114:117], v[66:81]
	v_add_u32_e32 v190, v0, v174
	ds_read_b128 v[186:189], v190 offset:32768
	ds_read_b128 v[190:193], v190 offset:40960
	v_mfma_f32_32x32x16_bf16 v[82:97], v[178:181], v[118:121], v[82:97]
	v_mfma_f32_32x32x16_bf16 v[66:81], v[182:185], v[118:121], v[66:81]
	v_add_u32_e32 v0, v0, v175
	ds_read_b128 v[178:181], v0 offset:32768
	ds_read_b128 v[182:185], v0 offset:40960
	s_waitcnt lgkmcnt(0)
; template <int MODE>
; __device__ __forceinline__ void att_smpv(f32x16 (&s)[2], f32x16 (&o)[4], float& mrun, float& lrun, float& Rrun, int tq, int tqmin, int tok0, int st, int dil, int h, int lane, const LAS unsigned char* vb) {
;     ...
;         const bool need_mask = (MODE == 0) || (tok0 + 63 > tqmin);
;         if (need_mask) {
; #pragma unroll
;             for (int kk = 0; kk < 2; ++kk)
; #pragma unroll
;                 for (int e = 0; e < 16; ++e) { const int d = d0 - st * (32 * kk + 8 * (e >> 2) + (e & 3));
;                     const bool ok = (MODE == 0) ? ((unsigned)d <= 128u * (unsigned)dil && (d & (dil - 1)) == 0) : (d >= 0);
;                     s[kk][e] = ok ? s[kk][e] : -INFINITY; }
;         }
;         float mx = fmaxf(fmaxf(s[0][0], s[1][0]), fmaxf(s[0][1], s[1][1]));
; #pragma unroll
;         for (int e = 2; e < 16; e += 2) { mx = fmaxf(fmaxf(mx, s[0][e]), s[1][e]); mx = fmaxf(fmaxf(mx, s[0][e + 1]), s[1][e + 1]); }
;         mx = fmaxf(mx, xhalf(mx, h));
;         if (__any(mx > mrun)) {
;             const float mnew = fmaxf(mrun, mx), alpha = __builtin_amdgcn_exp2f(mrun - mnew); mrun = mnew; lrun *= alpha;
; #pragma unroll
;             for (int b = 0; b < 4; ++b)
; #pragma unroll
;                 for (int e = 0; e < 16; ++e) o[b][e] *= alpha;
;         }
	v_mfma_f32_32x32x16_bf16 v[82:97], v[186:189], v[122:125], v[82:97]
	v_mfma_f32_32x32x16_bf16 v[66:81], v[190:193], v[122:125], v[66:81]
	v_mfma_f32_32x32x16_bf16 v[82:97], v[178:181], v[126:129], v[82:97]
	v_mfma_f32_32x32x16_bf16 v[66:81], v[182:185], v[126:129], v[66:81]
	v_subrev_u32_e32 v180, s8, v130
	v_mul_u32_u24_e32 v0, s28, v135
	s_add_i32 s5, s28, -1
	v_sub_u32_e32 v244, v180, v0
	s_ff1_i32_b32 s29, s28
	v_and_b32_e32 v245, s5, v244
	v_lshrrev_b32_e32 v244, s29, v244
	v_cmp_eq_u32_e32 vcc, 0, v245
	s_movk_i32 s29, 0x80
	v_mov_b32_e32 v245, 0x7fffffff
	s_nop 0
	v_cndmask_b32_e32 v244, v245, v244, vcc
	v_subrev_u32_e32 v245, 0, v244
	v_cmp_ge_u32_e32 vcc, s29, v245
	v_subrev_u32_e32 v246, 1, v244
	v_cmp_ge_u32_e64 s[8:9], s29, v246
	v_cndmask_b32_e32 v0, v214, v82, vcc
	v_subrev_u32_e32 v245, 2, v244
	v_cmp_ge_u32_e32 vcc, s29, v245
	v_cndmask_b32_e64 v83, v214, v83, s[8:9]
	v_subrev_u32_e32 v246, 3, v244
	v_cmp_ge_u32_e64 s[8:9], s29, v246
	v_cndmask_b32_e32 v82, v214, v84, vcc
	v_subrev_u32_e32 v245, 8, v244
	v_cmp_ge_u32_e32 vcc, s29, v245
	v_cndmask_b32_e64 v85, v214, v85, s[8:9]
	v_subrev_u32_e32 v246, 9, v244
	v_cmp_ge_u32_e64 s[8:9], s29, v246
	v_cndmask_b32_e32 v84, v214, v86, vcc
	v_subrev_u32_e32 v245, 10, v244
	v_cmp_ge_u32_e32 vcc, s29, v245
	v_cndmask_b32_e64 v87, v214, v87, s[8:9]
	v_subrev_u32_e32 v246, 11, v244
	v_cmp_ge_u32_e64 s[8:9], s29, v246
	v_cndmask_b32_e32 v86, v214, v88, vcc
	v_subrev_u32_e32 v245, 16, v244
	v_cmp_ge_u32_e32 vcc, s29, v245
	v_cndmask_b32_e64 v89, v214, v89, s[8:9]
	v_subrev_u32_e32 v246, 17, v244
	v_cmp_ge_u32_e64 s[8:9], s29, v246
	v_cndmask_b32_e32 v88, v214, v90, vcc
	v_subrev_u32_e32 v245, 18, v244
	v_cmp_ge_u32_e32 vcc, s29, v245
	v_cndmask_b32_e64 v91, v214, v91, s[8:9]
	v_subrev_u32_e32 v246, 19, v244
	v_cmp_ge_u32_e64 s[8:9], s29, v246
	v_cndmask_b32_e32 v90, v214, v92, vcc
	v_subrev_u32_e32 v245, 24, v244
	v_cmp_ge_u32_e32 vcc, s29, v245
	v_cndmask_b32_e64 v93, v214, v93, s[8:9]
	v_subrev_u32_e32 v246, 25, v244
	v_cmp_ge_u32_e64 s[8:9], s29, v246
	v_cndmask_b32_e32 v92, v214, v94, vcc
	v_subrev_u32_e32 v245, 26, v244
	v_cmp_ge_u32_e32 vcc, s29, v245
	v_cndmask_b32_e64 v95, v214, v95, s[8:9]
	v_subrev_u32_e32 v246, 27, v244
	v_cmp_ge_u32_e64 s[8:9], s29, v246
	v_cndmask_b32_e32 v94, v214, v96, vcc
	v_subrev_u32_e32 v245, 32, v244
	v_cmp_ge_u32_e32 vcc, s29, v245
	v_cndmask_b32_e64 v96, v214, v97, s[8:9]
	v_subrev_u32_e32 v246, 33, v244
	v_cmp_ge_u32_e64 s[8:9], s29, v246
	v_cndmask_b32_e32 v66, v214, v66, vcc
	v_subrev_u32_e32 v245, 34, v244
	v_cmp_ge_u32_e32 vcc, s29, v245
	v_cndmask_b32_e64 v97, v214, v67, s[8:9]
	v_subrev_u32_e32 v246, 35, v244
	v_cmp_ge_u32_e64 s[8:9], s29, v246
	v_cndmask_b32_e32 v67, v214, v68, vcc
	v_subrev_u32_e32 v245, 40, v244
	v_cmp_ge_u32_e32 vcc, s29, v245
	v_cndmask_b32_e64 v178, v214, v69, s[8:9]
	v_subrev_u32_e32 v246, 41, v244
	v_cmp_ge_u32_e64 s[8:9], s29, v246
	v_cndmask_b32_e32 v68, v214, v70, vcc
	v_subrev_u32_e32 v245, 42, v244
	v_cmp_ge_u32_e32 vcc, s29, v245
	v_cndmask_b32_e64 v179, v214, v71, s[8:9]
	v_subrev_u32_e32 v246, 43, v244
	v_cmp_ge_u32_e64 s[8:9], s29, v246
	v_cndmask_b32_e32 v69, v214, v72, vcc
	v_subrev_u32_e32 v245, 48, v244
	v_cmp_ge_u32_e32 vcc, s29, v245
	v_cndmask_b32_e64 v73, v214, v73, s[8:9]
	v_subrev_u32_e32 v246, 49, v244
	v_cmp_ge_u32_e64 s[8:9], s29, v246
	v_cndmask_b32_e32 v70, v214, v74, vcc
	v_subrev_u32_e32 v245, 50, v244
	v_cmp_ge_u32_e32 vcc, s29, v245
	v_cndmask_b32_e64 v75, v214, v75, s[8:9]
	v_subrev_u32_e32 v246, 51, v244
	v_cmp_ge_u32_e64 s[8:9], s29, v246
	v_cndmask_b32_e32 v71, v214, v76, vcc
	v_subrev_u32_e32 v245, 56, v244
	v_cmp_ge_u32_e32 vcc, s29, v245
	v_cndmask_b32_e64 v76, v214, v77, s[8:9]
	v_subrev_u32_e32 v246, 57, v244
	v_cmp_ge_u32_e64 s[8:9], s29, v246
	v_cndmask_b32_e32 v72, v214, v78, vcc
	v_subrev_u32_e32 v245, 58, v244
	v_cmp_ge_u32_e32 vcc, s29, v245
	v_cndmask_b32_e64 v77, v214, v79, s[8:9]
	v_subrev_u32_e32 v246, 59, v244
	v_cmp_ge_u32_e64 s[8:9], s29, v246
	v_cndmask_b32_e32 v74, v214, v80, vcc
	s_nop 1
	v_cndmask_b32_e64 v78, v214, v81, s[8:9]
	s_mul_i32 s29, s28, 5
	v_max_f32_e32 v79, v97, v97
	v_max_f32_e32 v80, v83, v83
	v_max_f32_e32 v79, v80, v79
	v_max3_f32 v79, v0, v66, v79
	v_max3_f32 v79, v79, v82, v67
	v_max3_f32 v79, v79, v85, v178
	v_max3_f32 v79, v79, v84, v68
	v_max3_f32 v79, v79, v87, v179
	v_max3_f32 v79, v79, v86, v69
	v_max3_f32 v79, v79, v89, v73
	v_max3_f32 v79, v79, v88, v70
	v_max3_f32 v79, v79, v91, v75
	v_max3_f32 v79, v79, v90, v71
	v_max3_f32 v79, v79, v93, v76
	v_max3_f32 v79, v79, v92, v72
	v_max3_f32 v79, v79, v95, v77
	v_max3_f32 v79, v79, v94, v74
	v_max3_f32 v79, v79, v96, v78
	v_mov_b32_e32 v80, v79
	v_mov_b32_e32 v81, v79
	s_nop 1
	v_permlane32_swap_b32_e32 v80, v81
	v_cndmask_b32_e64 v80, v80, v81, s[6:7]
	v_max_f32_e32 v80, v80, v80
	v_max_f32_e32 v79, v79, v80
	v_cmp_gt_f32_e32 vcc, v79, v177
	s_cbranch_vccz .LBB0_309
	v_max_f32_e32 v79, v79, v79
	v_max_f32_e32 v80, v177, v177
	v_max_f32_e32 v79, v80, v79
	v_sub_f32_e32 v80, v177, v79
	v_exp_f32_e32 v80, v80
	v_mov_b32_e32 v177, v79
	v_mul_f32_e32 v176, v176, v80
	v_pk_mul_f32 v[64:65], v[64:65], v[80:81] op_sel_hi:[1,0]
	v_pk_mul_f32 v[62:63], v[62:63], v[80:81] op_sel_hi:[1,0]
	v_pk_mul_f32 v[60:61], v[60:61], v[80:81] op_sel_hi:[1,0]
	v_pk_mul_f32 v[58:59], v[58:59], v[80:81] op_sel_hi:[1,0]
	v_pk_mul_f32 v[56:57], v[56:57], v[80:81] op_sel_hi:[1,0]
	v_pk_mul_f32 v[54:55], v[54:55], v[80:81] op_sel_hi:[1,0]
	v_pk_mul_f32 v[52:53], v[52:53], v[80:81] op_sel_hi:[1,0]
	v_pk_mul_f32 v[50:51], v[50:51], v[80:81] op_sel_hi:[1,0]
	v_pk_mul_f32 v[48:49], v[48:49], v[80:81] op_sel_hi:[1,0]
	v_pk_mul_f32 v[46:47], v[46:47], v[80:81] op_sel_hi:[1,0]
	v_pk_mul_f32 v[44:45], v[44:45], v[80:81] op_sel_hi:[1,0]
	v_pk_mul_f32 v[42:43], v[42:43], v[80:81] op_sel_hi:[1,0]
	v_pk_mul_f32 v[40:41], v[40:41], v[80:81] op_sel_hi:[1,0]
	v_pk_mul_f32 v[38:39], v[38:39], v[80:81] op_sel_hi:[1,0]
	v_pk_mul_f32 v[36:37], v[36:37], v[80:81] op_sel_hi:[1,0]
	v_pk_mul_f32 v[34:35], v[34:35], v[80:81] op_sel_hi:[1,0]
	v_pk_mul_f32 v[32:33], v[32:33], v[80:81] op_sel_hi:[1,0]
	v_pk_mul_f32 v[30:31], v[30:31], v[80:81] op_sel_hi:[1,0]
	v_pk_mul_f32 v[28:29], v[28:29], v[80:81] op_sel_hi:[1,0]
	v_pk_mul_f32 v[26:27], v[26:27], v[80:81] op_sel_hi:[1,0]
	v_pk_mul_f32 v[24:25], v[24:25], v[80:81] op_sel_hi:[1,0]
	v_pk_mul_f32 v[22:23], v[22:23], v[80:81] op_sel_hi:[1,0]
	v_pk_mul_f32 v[20:21], v[20:21], v[80:81] op_sel_hi:[1,0]
	v_pk_mul_f32 v[18:19], v[18:19], v[80:81] op_sel_hi:[1,0]
	v_pk_mul_f32 v[16:17], v[16:17], v[80:81] op_sel_hi:[1,0]
	v_pk_mul_f32 v[14:15], v[14:15], v[80:81] op_sel_hi:[1,0]
	v_pk_mul_f32 v[12:13], v[12:13], v[80:81] op_sel_hi:[1,0]
	v_pk_mul_f32 v[10:11], v[10:11], v[80:81] op_sel_hi:[1,0]
	v_pk_mul_f32 v[8:9], v[8:9], v[80:81] op_sel_hi:[1,0]
	v_pk_mul_f32 v[6:7], v[6:7], v[80:81] op_sel_hi:[1,0]
	v_pk_mul_f32 v[4:5], v[4:5], v[80:81] op_sel_hi:[1,0]
	v_pk_mul_f32 v[2:3], v[2:3], v[80:81] op_sel_hi:[1,0]
